# code placement: G2 and G4 K-loop heads moved from 4-mod-8 to 8-byte-aligned offsets (three pad s_nop)
# speedup vs baseline: 1.0026x; 1.0026x over previous
.LBB0_762:
	s_ashr_i32 s17, s16, 31
	s_lshl_b64 s[2:3], s[16:17], 19
	s_add_u32 s24, s4, s2
	s_addc_u32 s25, s5, s3
	s_and_b64 s[0:1], s[0:1], exec
	s_cselect_b32 s17, s25, s7
	s_cselect_b32 s40, s24, s6
	s_add_u32 s41, s6, 0x100
	s_addc_u32 s56, s7, 0
	s_mov_b32 s57, -2
	s_nop 0

.LBB0_861:
	s_ashr_i32 s17, s16, 31
	s_lshl_b64 s[2:3], s[16:17], 19
	s_add_u32 s18, s0, s2
	s_addc_u32 s19, s1, s3
	s_and_b64 s[2:3], s[8:9], exec
	s_cselect_b32 s17, s19, s7
	s_cselect_b32 s39, s18, s6
	s_ashr_i32 s15, s14, 31
	s_lshl_b64 s[2:3], s[14:15], 19
	s_add_u32 s24, s4, s2
	s_addc_u32 s25, s5, s3
	s_and_b64 s[2:3], s[8:9], exec
	s_cselect_b32 s15, s25, s23
	s_cselect_b32 s40, s24, s22
	s_add_u32 s22, s22, 0x100
	s_addc_u32 s23, s23, 0
	s_add_u32 s6, s6, 0x40080
	s_addc_u32 s7, s7, 0
	s_mov_b32 s41, -2
	s_nop 0

.LBB0_1061:
	s_add_u32 s39, s18, 0x100
	s_addc_u32 s40, s19, 0
	s_mov_b32 s41, -2
	s_nop 0
